# speedup vs baseline: 1.0791x; 1.0257x over previous
; DEVI void phase0(const Params& p, char* shm) {
;   int tid = threadIdx.x;
;   asm volatile("" : "+v"(tid));
;   const int wid = tid >> 6, lane = tid & 63;
;   char* ws = p.ws;
;   {
;     const int total = 1024 + 256 + 1408 + 1408 + 704 + 704 + 1024 + 256;
;     float v[8];
;     CvtDesc d;
;     int it = blockIdx.x;
;     if (it < total) { cvt_decode(p, it, d); cvt_load(d, v); }
;     int par = 0;
;     while (it < total) {
;       float* tile = (float*)shm + par * (64 * 65); par ^= 1;
.LBB0_57:
	v_ashrrev_i32_e32 v20, 6, v10
	s_andn2_b64 vcc, exec, s[6:7]
	v_and_b32_e32 v50, 63, v10
	s_cbranch_vccnz .LBB0_108
	s_load_dword s0, s[76:77], 0x10
	v_bfe_u32 v21, v220, 4, 1
	v_lshlrev_b32_e32 v12, 1, v220
	v_and_b32_e32 v12, 24, v12
	v_lshlrev_b32_e32 v13, 2, v21
	s_waitcnt lgkmcnt(0)
	s_lshr_b32 s0, s0, 16
	s_cmp_lg_u32 s0, 0
	s_cselect_b64 s[0:1], -1, 0
	s_cmp_lg_u64 s[0:1], 0
	s_addc_u32 s85, s3, 0
	s_add_u32 s6, s74, 0x3300000
	s_addc_u32 s7, s75, 0
	s_add_u32 s8, s44, 0x1000
	s_addc_u32 s9, s45, 0
	s_add_u32 s10, s74, 0x2b00000
	s_addc_u32 s11, s75, 0
	s_add_u32 s12, s70, 0xb00000
	s_addc_u32 s13, s71, 0
	s_add_u32 s14, s74, 0x2580000
	s_addc_u32 s15, s75, 0
	s_add_u32 s16, s74, 0x2000000
	s_addc_u32 s17, s75, 0
	s_add_u32 s18, s68, 0x1600000
	s_addc_u32 s19, s69, 0
	s_add_u32 s20, s46, 0x1000
	s_addc_u32 s21, s47, 0
	s_add_u32 s22, s74, 0x1500000
	s_addc_u32 s23, s75, 0
	v_and_b32_e32 v14, 3, v220
	s_add_u32 s24, s74, 0xa00000
	v_or3_b32 v23, v13, v12, v14
	v_lshlrev_b32_e32 v12, 3, v10
	s_addc_u32 s25, s75, 0
	v_ashrrev_i32_e32 v24, 3, v10
	v_and_b32_e32 v12, 56, v12
	s_movk_i32 s0, 0x104
	s_add_u32 s26, s74, 0x800000
	s_mov_b32 s84, 0
	v_and_b32_e32 v9, 32, v220
	v_lshrrev_b32_e32 v11, 6, v220
	v_and_b32_e32 v22, 15, v220
	v_mov_b32_e32 v13, 0
	v_mul_u32_u24_e32 v25, 0x104, v12
	v_mul_lo_u32 v26, v20, s0
	s_addc_u32 s27, s75, 0
	s_movk_i32 s86, 0x1c00
	v_lshlrev_b32_e32 v27, 2, v24
	v_lshlrev_b32_e32 v12, 1, v12
	s_mov_b32 s87, s2
	s_mov_b64 s[30:31], s[4:5]
	s_mov_b32 s89, s33
	s_mov_b32 s80, s82
	s_mov_b32 s81, s83
	v_mov_b32_e32 v84, 1.0
	v_mov_b32_e32 v85, 1.0
	v_mov_b32_e32 v86, 1.0
	v_mov_b32_e32 v87, 1.0
	v_mov_b32_e32 v88, 1.0
	v_mov_b32_e32 v89, 1.0
	v_mov_b32_e32 v90, 1.0
	v_mov_b32_e32 v91, 1.0
	s_branch .LBB0_60

; DEVI void phase0(const Params& p, char* shm) {
;     ...
;     while (it < total) {
;       float* tile = (float*)shm + par * (64 * 65); par ^= 1;
;       const int c = tid & 63, r0 = tid >> 6;
; #pragma unroll
;       for (int i = 0; i < 8; ++i) tile[(r0 + 8 * i) * 65 + c] = v[i];
;       const CvtDesc dc = d;
;       const int itn = it + gridDim.x;
;       if (itn < total) { cvt_decode(p, itn, d); cvt_load(d, v); }
;       __syncthreads();
.LBB0_60:
	s_add_i32 s87, s87, s85
	s_mul_i32 s88, s84, 0x4100
	s_cmpk_gt_i32 s87, 0x1a7f
	v_lshl_or_b32 v14, v50, 2, s88
	s_cselect_b64 s[28:29], -1, 0
	v_add_u32_e32 v14, v14, v26
	s_and_b64 vcc, exec, s[28:29]
	s_waitcnt vmcnt(0)
	v_mul_f32_e32 v2, v2, v84
	ds_write_b32 v14, v2
	v_mul_f32_e32 v1, v1, v85
	ds_write_b32 v14, v1 offset:2080
	v_mul_f32_e32 v4, v4, v86
	ds_write_b32 v14, v4 offset:4160
	v_mul_f32_e32 v3, v3, v87
	ds_write_b32 v14, v3 offset:6240
	v_mul_f32_e32 v6, v6, v88
	ds_write_b32 v14, v6 offset:8320
	v_mul_f32_e32 v5, v5, v89
	ds_write_b32 v14, v5 offset:10400
	v_mul_f32_e32 v8, v8, v90
	ds_write_b32 v14, v8 offset:12480
	v_mul_f32_e32 v7, v7, v91
	ds_write_b32 v14, v7 offset:14560
	s_cbranch_vccnz .LBB0_59
	s_cmpk_lt_i32 s87, 0x400
	s_movk_i32 s89, 0x400
	s_cbranch_scc1 .LBB0_69
	s_cmpk_gt_u32 s87, 0x4ff
	s_cbranch_scc0 .LBB0_70
	s_cmpk_gt_u32 s87, 0xa7f
	s_cbranch_scc0 .LBB0_93
	s_cmpk_gt_u32 s87, 0xfff
	s_mov_b64 s[78:79], -1
	s_cbranch_scc1 .LBB0_94
	s_mov_b64 s[80:81], 0
	s_andn2_b64 vcc, exec, s[78:79]
	s_mov_b64 s[78:79], 0
	s_cbranch_vccz .LBB0_106

; DEVI void cvt_load(const CvtDesc& d, float (&v)[8]) {
;   const int tid = threadIdx.x, c = tid & 63, r0 = tid >> 6;
;   const int col = colmap(d.mode, d.pt * 64 + c);
; #pragma unroll
;   for (int i = 0; i < 8; ++i) {
;     const int r = d.kt * 64 + r0 + 8 * i;
;     float x = __builtin_nontemporal_load(d.src + (size_t)r * d.ld + col);
;     if (d.gain) x *= d.gain[r];
;     v[i] = x;
;   }
; }
.LBB0_77:
	v_lshl_or_b32 v16, s80, 6, v11
	v_ashrrev_i32_e32 v3, 31, v2
	v_ashrrev_i32_e32 v17, 31, v16
	v_lshl_add_u64 v[14:15], v[2:3], 2, s[0:1]
	v_mul_lo_u32 v1, s34, v17
	v_mul_lo_u32 v4, s35, v16
	v_mad_u64_u32 v[2:3], s[0:1], s34, v16, 0
	v_add3_u32 v3, v3, v1, v4
	v_lshl_add_u64 v[2:3], v[2:3], 2, v[14:15]
	global_load_dword v2, v[2:3], off nt
	s_cmp_lg_u64 s[36:37], 0
	s_cselect_b64 s[38:39], -1, 0
	s_cmp_eq_u64 s[36:37], 0
	v_lshl_add_u64 v[18:19], v[16:17], 2, s[36:37]
	v_add_u32_e32 v1, 8, v16
	v_ashrrev_i32_e32 v3, 31, v1
	v_mul_lo_u32 v3, s34, v3
	v_mul_lo_u32 v6, s35, v1
	v_mad_u64_u32 v[4:5], s[0:1], s34, v1, 0
	v_add3_u32 v5, v5, v3, v6
	v_lshl_add_u64 v[4:5], v[4:5], 2, v[14:15]
	global_load_dword v1, v[4:5], off nt
	v_cndmask_b32_e64 v3, 0, 1, s[38:39]
	v_cmp_ne_u32_e64 s[0:1], 1, v3
	v_or_b32_e32 v3, 16, v16
	v_mul_lo_u32 v7, s34, v17
	v_mul_lo_u32 v6, s35, v3
	v_mad_u64_u32 v[4:5], s[36:37], s34, v3, 0
	v_add3_u32 v5, v5, v7, v6
	v_lshl_add_u64 v[4:5], v[4:5], 2, v[14:15]
	global_load_dword v4, v[4:5], off nt
	v_add_u32_e32 v3, 24, v16
	v_ashrrev_i32_e32 v5, 31, v3
	v_mul_lo_u32 v5, s34, v5
	v_mul_lo_u32 v6, s35, v3
	v_mad_u64_u32 v[28:29], s[36:37], s34, v3, 0
	v_add3_u32 v29, v29, v5, v6
	v_lshl_add_u64 v[28:29], v[28:29], 2, v[14:15]
	global_load_dword v3, v[28:29], off nt
	v_or_b32_e32 v5, 32, v16
	v_mul_lo_u32 v6, s35, v5
	v_mad_u64_u32 v[28:29], s[36:37], s34, v5, 0
	v_add3_u32 v29, v29, v7, v6
	v_lshl_add_u64 v[28:29], v[28:29], 2, v[14:15]
	global_load_dword v6, v[28:29], off nt
	v_add_u32_e32 v5, 40, v16
	v_ashrrev_i32_e32 v8, 31, v5
	v_mul_lo_u32 v8, s34, v8
	v_mul_lo_u32 v17, s35, v5
	v_mad_u64_u32 v[28:29], s[36:37], s34, v5, 0
	v_add3_u32 v29, v29, v8, v17
	v_lshl_add_u64 v[28:29], v[28:29], 2, v[14:15]
	global_load_dword v5, v[28:29], off nt
	v_or_b32_e32 v8, 48, v16
	v_mul_lo_u32 v17, s35, v8
	v_mad_u64_u32 v[28:29], s[36:37], s34, v8, 0
	v_add3_u32 v29, v29, v7, v17
	v_lshl_add_u64 v[28:29], v[28:29], 2, v[14:15]
	global_load_dword v8, v[28:29], off nt
	v_add_u32_e32 v7, 56, v16
	v_ashrrev_i32_e32 v16, 31, v7
	v_mul_lo_u32 v28, s34, v16
	v_mul_lo_u32 v29, s35, v7
	v_mad_u64_u32 v[16:17], s[34:35], s34, v7, 0
	v_add3_u32 v17, v17, v28, v29
	v_lshl_add_u64 v[14:15], v[16:17], 2, v[14:15]
	global_load_dword v7, v[14:15], off nt
	s_cmp_eq_u64 s[38:39], 0
	s_cbranch_scc1 .Lp0_nogain
	global_load_dword v84, v[18:19], off
	global_load_dword v85, v[18:19], off offset:32
	global_load_dword v86, v[18:19], off offset:64
	global_load_dword v87, v[18:19], off offset:96
	global_load_dword v88, v[18:19], off offset:128
	global_load_dword v89, v[18:19], off offset:160
	global_load_dword v90, v[18:19], off offset:192
	global_load_dword v91, v[18:19], off offset:224
	s_branch .LBB0_59
.Lp0_nogain:
	v_mov_b32_e32 v84, 1.0
	v_mov_b32_e32 v85, 1.0
	v_mov_b32_e32 v86, 1.0
	v_mov_b32_e32 v87, 1.0
	v_mov_b32_e32 v88, 1.0
	v_mov_b32_e32 v89, 1.0
	v_mov_b32_e32 v90, 1.0
	v_mov_b32_e32 v91, 1.0
	s_branch .LBB0_59
